# GEMM k-loops: static s_setprio 1 for waves 4-7 inside the hand-written loop (on v10 base)
# baseline (speedup 1.0000x reference)
.LBB0_178:
	s_or_b64 exec, exec, s[10:11]
	v_readlane_b32 s12, v250, 9
	v_readlane_b32 s14, v250, 11
	v_readlane_b32 s15, v250, 12
	s_add_u32 s8, s14, s8
	s_addc_u32 s9, s15, s9
	s_add_u32 s10, s14, s0
	v_mov_b32_e32 v98, 0
	s_addc_u32 s11, s15, s1
	s_mov_b32 s3, 0
	v_add_u32_e32 v176, 0x18000, v174
	v_mov_b32_e32 v99, v98
	v_mov_b32_e32 v100, v98
	v_mov_b32_e32 v101, v98
	v_mov_b32_e32 v102, v98
	v_mov_b32_e32 v103, v98
	v_mov_b32_e32 v104, v98
	v_mov_b32_e32 v105, v98
	v_mov_b32_e32 v106, v98
	v_mov_b32_e32 v107, v98
	v_mov_b32_e32 v108, v98
	v_mov_b32_e32 v109, v98
	v_mov_b32_e32 v110, v98
	v_mov_b32_e32 v111, v98
	v_mov_b32_e32 v112, v98
	v_mov_b32_e32 v113, v98
	v_mov_b32_e32 v66, v98
	v_mov_b32_e32 v67, v98
	v_mov_b32_e32 v68, v98
	v_mov_b32_e32 v69, v98
	v_mov_b32_e32 v70, v98
	v_mov_b32_e32 v71, v98
	v_mov_b32_e32 v72, v98
	v_mov_b32_e32 v73, v98
	v_mov_b32_e32 v74, v98
	v_mov_b32_e32 v75, v98
	v_mov_b32_e32 v76, v98
	v_mov_b32_e32 v77, v98
	v_mov_b32_e32 v78, v98
	v_mov_b32_e32 v79, v98
	v_mov_b32_e32 v80, v98
	v_mov_b32_e32 v81, v98
	v_mov_b32_e32 v34, v98
	v_mov_b32_e32 v35, v98
	v_mov_b32_e32 v36, v98
	v_mov_b32_e32 v37, v98
	v_mov_b32_e32 v38, v98
	v_mov_b32_e32 v39, v98
	v_mov_b32_e32 v40, v98
	v_mov_b32_e32 v41, v98
	v_mov_b32_e32 v42, v98
	v_mov_b32_e32 v43, v98
	v_mov_b32_e32 v44, v98
	v_mov_b32_e32 v45, v98
	v_mov_b32_e32 v46, v98
	v_mov_b32_e32 v47, v98
	v_mov_b32_e32 v48, v98
	v_mov_b32_e32 v49, v98
	v_mov_b32_e32 v2, v98
	v_mov_b32_e32 v3, v98
	v_mov_b32_e32 v4, v98
	v_mov_b32_e32 v5, v98
	v_mov_b32_e32 v6, v98
	v_mov_b32_e32 v7, v98
	v_mov_b32_e32 v8, v98
	v_mov_b32_e32 v9, v98
	v_mov_b32_e32 v10, v98
	v_mov_b32_e32 v11, v98
	v_mov_b32_e32 v12, v98
	v_mov_b32_e32 v13, v98
	v_mov_b32_e32 v14, v98
	v_mov_b32_e32 v15, v98
	v_mov_b32_e32 v16, v98
	v_mov_b32_e32 v17, v98
	v_mov_b32_e32 v114, v98
	v_mov_b32_e32 v115, v98
	v_mov_b32_e32 v116, v98
	v_mov_b32_e32 v117, v98
	v_mov_b32_e32 v118, v98
	v_mov_b32_e32 v119, v98
	v_mov_b32_e32 v120, v98
	v_mov_b32_e32 v121, v98
	v_mov_b32_e32 v122, v98
	v_mov_b32_e32 v123, v98
	v_mov_b32_e32 v124, v98
	v_mov_b32_e32 v125, v98
	v_mov_b32_e32 v126, v98
	v_mov_b32_e32 v127, v98
	v_mov_b32_e32 v128, v98
	v_mov_b32_e32 v129, v98
	v_mov_b32_e32 v82, v98
	v_mov_b32_e32 v83, v98
	v_mov_b32_e32 v84, v98
	v_mov_b32_e32 v85, v98
	v_mov_b32_e32 v86, v98
	v_mov_b32_e32 v87, v98
	v_mov_b32_e32 v88, v98
	v_mov_b32_e32 v89, v98
	v_mov_b32_e32 v90, v98
	v_mov_b32_e32 v91, v98
	v_mov_b32_e32 v92, v98
	v_mov_b32_e32 v93, v98
	v_mov_b32_e32 v94, v98
	v_mov_b32_e32 v95, v98
	v_mov_b32_e32 v96, v98
	v_mov_b32_e32 v97, v98
	v_mov_b32_e32 v50, v98
	v_mov_b32_e32 v51, v98
	v_mov_b32_e32 v52, v98
	v_mov_b32_e32 v53, v98
	v_mov_b32_e32 v54, v98
	v_mov_b32_e32 v55, v98
	v_mov_b32_e32 v56, v98
	v_mov_b32_e32 v57, v98
	v_mov_b32_e32 v58, v98
	v_mov_b32_e32 v59, v98
	v_mov_b32_e32 v60, v98
	v_mov_b32_e32 v61, v98
	v_mov_b32_e32 v62, v98
	v_mov_b32_e32 v63, v98
	v_mov_b32_e32 v64, v98
	v_mov_b32_e32 v65, v98
	v_mov_b32_e32 v18, v98
	v_mov_b32_e32 v19, v98
	v_mov_b32_e32 v20, v98
	v_mov_b32_e32 v21, v98
	v_mov_b32_e32 v22, v98
	v_mov_b32_e32 v23, v98
	v_mov_b32_e32 v24, v98
	v_mov_b32_e32 v25, v98
	v_mov_b32_e32 v26, v98
	v_mov_b32_e32 v27, v98
	v_mov_b32_e32 v28, v98
	v_mov_b32_e32 v29, v98
	v_mov_b32_e32 v30, v98
	v_mov_b32_e32 v31, v98
	v_mov_b32_e32 v32, v98
	v_mov_b32_e32 v33, v98
	v_readlane_b32 s13, v250, 10
	s_add_u32 s18, s8, 0x5800080
	s_addc_u32 s19, s9, 0
	s_add_u32 s20, s18, 0x20000
	s_addc_u32 s21, s19, 0
	s_add_u32 s22, s18, 0x40000
	s_addc_u32 s23, s19, 0
	s_add_u32 s24, s18, 0x60000
	s_addc_u32 s25, s19, 0
	s_add_u32 s8, s10, 0x5100080
	s_addc_u32 s9, s11, 0
	s_add_u32 s10, s8, 0x20000
	s_addc_u32 s11, s9, 0
	s_add_u32 s12, s8, 0x40000
	s_addc_u32 s13, s9, 0
	s_add_u32 s14, s8, 0x60000
	s_addc_u32 s15, s9, 0
	v_lshrrev_b32_e32 v170, 3, v204
	v_lshrrev_b32_e32 v171, 4, v204
	v_xor_b32_e32 v171, v171, v204
	v_and_b32_e32 v171, 7, v171
	v_lshlrev_b32_e32 v171, 4, v171
	v_lshl_or_b32 v170, v170, 11, v171
	v_readfirstlane_b32 s26, v204
	s_and_b32 s26, s26, 0x3c0
	s_lshl_b32 s26, s26, 4
	s_mov_b32 s3, 0
	s_cmp_ge_u32 s26, 0x1000
	s_cbranch_scc0 .Lg_cin_noprio
	s_setprio 1
.Lg_cin_noprio:
	ds_read_b128 v[130:133], v225
	ds_read_b128 v[138:141], v226
	ds_read_b128 v[134:137], v225 offset:4096
	ds_read_b128 v[142:145], v226 offset:4096
	ds_read_b128 v[146:149], v226 offset:8192
	ds_read_b128 v[150:153], v226 offset:12288
	s_add_u32 m0, s26, 0x8000
	s_nop 0
	global_load_lds_dwordx4 v170, s[8:9]
	s_add_u32 m0, s26, 0x18000
	s_nop 0
	global_load_lds_dwordx4 v170, s[18:19]
	s_add_u32 m0, s26, 0xa000
	s_nop 0
	global_load_lds_dwordx4 v170, s[10:11]
	s_add_u32 m0, s26, 0x1a000
	s_nop 0
	global_load_lds_dwordx4 v170, s[20:21]
	s_add_u32 m0, s26, 0xc000
	s_nop 0
	global_load_lds_dwordx4 v170, s[12:13]
	s_add_u32 m0, s26, 0x1c000
	s_nop 0
	global_load_lds_dwordx4 v170, s[22:23]
	s_add_u32 m0, s26, 0xe000
	s_nop 0
	global_load_lds_dwordx4 v170, s[14:15]
	s_add_u32 m0, s26, 0x1e000
	s_nop 0
	global_load_lds_dwordx4 v170, s[24:25]
	s_branch .Lg_cin_mid

.Lg_cin_join:
	ds_read_b128 v[154:157], v227 offset:32768
	ds_read_b128 v[162:165], v235
	ds_read_b128 v[158:161], v227 offset:36864
	ds_read_b128 v[166:169], v235 offset:4096
	ds_read_b128 v[178:181], v235 offset:8192
	ds_read_b128 v[182:185], v235 offset:12288
	s_waitcnt lgkmcnt(6)
	v_mfma_f32_32x32x16_bf16 v[98:113], v[130:133], v[138:141], v[98:113]
	s_add_u32 s8, s8, 0x80
	s_addc_u32 s9, s9, 0
	v_mfma_f32_32x32x16_bf16 v[114:129], v[134:137], v[138:141], v[114:129]
	s_add_u32 s10, s10, 0x80
	s_addc_u32 s11, s11, 0
	v_mfma_f32_32x32x16_bf16 v[66:81], v[130:133], v[142:145], v[66:81]
	s_add_u32 s12, s12, 0x80
	s_addc_u32 s13, s13, 0
	v_mfma_f32_32x32x16_bf16 v[82:97], v[134:137], v[142:145], v[82:97]
	s_add_u32 s14, s14, 0x80
	s_addc_u32 s15, s15, 0
	v_mfma_f32_32x32x16_bf16 v[34:49], v[130:133], v[146:149], v[34:49]
	s_add_u32 s18, s18, 0x80
	s_addc_u32 s19, s19, 0
	v_mfma_f32_32x32x16_bf16 v[50:65], v[134:137], v[146:149], v[50:65]
	s_add_u32 s20, s20, 0x80
	s_addc_u32 s21, s21, 0
	v_mfma_f32_32x32x16_bf16 v[2:17], v[130:133], v[150:153], v[2:17]
	s_add_u32 s22, s22, 0x80
	s_addc_u32 s23, s23, 0
	v_mfma_f32_32x32x16_bf16 v[18:33], v[134:137], v[150:153], v[18:33]
	s_add_u32 s24, s24, 0x80
	s_addc_u32 s25, s25, 0
	ds_read_b128 v[130:133], v229 offset:32768
	ds_read_b128 v[138:141], v236
	ds_read_b128 v[134:137], v229 offset:36864
	ds_read_b128 v[142:145], v236 offset:4096
	ds_read_b128 v[146:149], v236 offset:8192
	ds_read_b128 v[150:153], v236 offset:12288
	s_waitcnt lgkmcnt(6)
	v_mfma_f32_32x32x16_bf16 v[98:113], v[154:157], v[162:165], v[98:113]
	v_mfma_f32_32x32x16_bf16 v[114:129], v[158:161], v[162:165], v[114:129]
	v_mfma_f32_32x32x16_bf16 v[66:81], v[154:157], v[166:169], v[66:81]
	v_mfma_f32_32x32x16_bf16 v[82:97], v[158:161], v[166:169], v[82:97]
	v_mfma_f32_32x32x16_bf16 v[34:49], v[154:157], v[178:181], v[34:49]
	v_mfma_f32_32x32x16_bf16 v[50:65], v[158:161], v[178:181], v[50:65]
	v_mfma_f32_32x32x16_bf16 v[2:17], v[154:157], v[182:185], v[2:17]
	v_mfma_f32_32x32x16_bf16 v[18:33], v[158:161], v[182:185], v[18:33]
	ds_read_b128 v[154:157], v231 offset:32768
	ds_read_b128 v[162:165], v237
	ds_read_b128 v[158:161], v231 offset:36864
	ds_read_b128 v[166:169], v237 offset:4096
	ds_read_b128 v[178:181], v237 offset:8192
	ds_read_b128 v[182:185], v237 offset:12288
	s_waitcnt lgkmcnt(6)
	v_mfma_f32_32x32x16_bf16 v[98:113], v[130:133], v[138:141], v[98:113]
	v_mfma_f32_32x32x16_bf16 v[114:129], v[134:137], v[138:141], v[114:129]
	v_mfma_f32_32x32x16_bf16 v[66:81], v[130:133], v[142:145], v[66:81]
	v_mfma_f32_32x32x16_bf16 v[82:97], v[134:137], v[142:145], v[82:97]
	v_mfma_f32_32x32x16_bf16 v[34:49], v[130:133], v[146:149], v[34:49]
	v_mfma_f32_32x32x16_bf16 v[50:65], v[134:137], v[146:149], v[50:65]
	v_mfma_f32_32x32x16_bf16 v[2:17], v[130:133], v[150:153], v[2:17]
	v_mfma_f32_32x32x16_bf16 v[18:33], v[134:137], v[150:153], v[18:33]
	s_waitcnt vmcnt(0) lgkmcnt(0)
	s_barrier
	s_add_i32 s3, s3, 2
	s_cmp_lt_u32 s3, 16
	s_cbranch_scc1 .Lg_cin_top
	v_mfma_f32_32x32x16_bf16 v[98:113], v[154:157], v[162:165], v[98:113]
	v_mfma_f32_32x32x16_bf16 v[114:129], v[158:161], v[162:165], v[114:129]
	v_mfma_f32_32x32x16_bf16 v[66:81], v[154:157], v[166:169], v[66:81]
	v_mfma_f32_32x32x16_bf16 v[82:97], v[158:161], v[166:169], v[82:97]
	v_mfma_f32_32x32x16_bf16 v[34:49], v[154:157], v[178:181], v[34:49]
	v_mfma_f32_32x32x16_bf16 v[50:65], v[158:161], v[178:181], v[50:65]
	v_mfma_f32_32x32x16_bf16 v[2:17], v[154:157], v[182:185], v[2:17]
	v_mfma_f32_32x32x16_bf16 v[18:33], v[158:161], v[182:185], v[18:33]
	s_nop 7
	s_nop 7
	s_setprio 0
	s_branch .LBB0_196

.LBB0_1123:
	s_bfe_u32 s4, s14, 0x20003
	s_lshr_b32 s0, s14, 5
	s_lshl_b32 s0, s0, 3
	s_and_b32 s1, s14, 7
	s_add_i32 s0, s0, s1
	s_lshl_b32 s2, s0, 8
	s_ashr_i32 s3, s2, 31
	s_ashr_i32 s5, s4, 31
	s_lshl_b64 s[0:1], s[4:5], 19
	s_lshl_b64 s[6:7], s[2:3], 11
	v_readlane_b32 s8, v252, 31
	v_readlane_b32 s9, v252, 32
	s_add_u32 s8, s8, s6
	v_mov_b32_e32 v34, v178
	s_addc_u32 s9, s9, s7
	v_readlane_b32 s3, v252, 49
	s_add_u32 s10, s3, s0
	v_lshlrev_b32_e32 v0, 4, v34
	v_readlane_b32 s3, v252, 50
	v_ashrrev_i32_e32 v35, 3, v34
	v_and_b32_e32 v0, 0x70, v0
	s_addc_u32 s11, s3, s1
	v_lshl_or_b32 v0, v35, 11, v0
	v_lshl_add_u64 v[26:27], s[10:11], 0, v[0:1]
	v_add_co_u32_e32 v10, vcc, s52, v26
	v_lshl_add_u64 v[28:29], s[8:9], 0, v[0:1]
	s_nop 0
	v_addc_co_u32_e32 v11, vcc, 0, v27, vcc
	v_add_co_u32_e32 v14, vcc, s52, v28
	global_load_dwordx4 v[2:5], v0, s[10:11]
	global_load_dwordx4 v[6:9], v0, s[8:9]
	v_addc_co_u32_e32 v15, vcc, 0, v29, vcc
	v_add_co_u32_e32 v18, vcc, s56, v26
	global_load_dwordx4 v[10:13], v[10:11], off
	s_nop 0
	global_load_dwordx4 v[14:17], v[14:15], off
	v_addc_co_u32_e32 v19, vcc, 0, v27, vcc
	v_add_co_u32_e32 v22, vcc, s56, v28
	v_readlane_b32 s8, v250, 9
	s_nop 0
	v_addc_co_u32_e32 v23, vcc, 0, v29, vcc
	v_add_co_u32_e32 v26, vcc, s57, v26
	global_load_dwordx4 v[18:21], v[18:19], off
	s_nop 0
	global_load_dwordx4 v[22:25], v[22:23], off
	v_addc_co_u32_e32 v27, vcc, 0, v27, vcc
	v_add_co_u32_e32 v30, vcc, s57, v28
	v_lshrrev_b32_e32 v36, 1, v35
	s_nop 0
	v_addc_co_u32_e32 v31, vcc, 0, v29, vcc
	global_load_dwordx4 v[26:29], v[26:27], off
	s_nop 0
	global_load_dwordx4 v[30:33], v[30:31], off
	v_readlane_b32 s10, v250, 11
	v_xor_b32_e32 v34, v36, v34
	v_readlane_b32 s11, v250, 12
	s_add_u32 s6, s10, s6
	v_lshlrev_b32_e32 v35, 7, v35
	v_lshlrev_b32_e32 v34, 4, v34
	s_addc_u32 s7, s11, s7
	v_mov_b32_e32 v82, 0
	v_and_or_b32 v198, v34, s55, v35
	v_readlane_b32 s9, v250, 10
	s_add_u32 s8, s10, s0
	s_mov_b32 s3, 0
	v_mov_b32_e32 v83, v82
	v_mov_b32_e32 v84, v82
	v_mov_b32_e32 v85, v82
	v_mov_b32_e32 v86, v82
	v_mov_b32_e32 v87, v82
	v_mov_b32_e32 v88, v82
	v_mov_b32_e32 v89, v82
	v_mov_b32_e32 v90, v82
	v_mov_b32_e32 v91, v82
	v_mov_b32_e32 v92, v82
	v_mov_b32_e32 v93, v82
	v_mov_b32_e32 v94, v82
	v_mov_b32_e32 v95, v82
	v_mov_b32_e32 v96, v82
	v_mov_b32_e32 v97, v82
	v_mov_b32_e32 v66, v82
	v_add_u32_e32 v199, 0x10000, v198
	s_addc_u32 s9, s11, s1
	v_mov_b32_e32 v67, v82
	v_mov_b32_e32 v68, v82
	v_mov_b32_e32 v69, v82
	v_mov_b32_e32 v70, v82
	v_mov_b32_e32 v71, v82
	v_mov_b32_e32 v72, v82
	v_mov_b32_e32 v73, v82
	v_mov_b32_e32 v74, v82
	v_mov_b32_e32 v75, v82
	v_mov_b32_e32 v76, v82
	v_mov_b32_e32 v77, v82
	v_mov_b32_e32 v78, v82
	v_mov_b32_e32 v79, v82
	v_mov_b32_e32 v80, v82
	v_mov_b32_e32 v81, v82
	v_mov_b32_e32 v114, v82
	v_mov_b32_e32 v115, v82
	s_waitcnt vmcnt(7)
	ds_write_b128 v198, v[2:5]
	s_waitcnt vmcnt(6)
	ds_write_b128 v199, v[6:9]
	s_waitcnt vmcnt(5)
	ds_write_b128 v198, v[10:13] offset:8192
	s_waitcnt vmcnt(4)
	ds_write_b128 v199, v[14:17] offset:8192
	s_waitcnt vmcnt(3)
	ds_write_b128 v198, v[18:21] offset:16384
	s_waitcnt vmcnt(2)
	ds_write_b128 v199, v[22:25] offset:16384
	s_waitcnt vmcnt(1)
	ds_write_b128 v198, v[26:29] offset:24576
	s_waitcnt vmcnt(0)
	ds_write_b128 v199, v[30:33] offset:24576
	v_mov_b32_e32 v18, v82
	v_mov_b32_e32 v19, v82
	v_mov_b32_e32 v20, v82
	v_mov_b32_e32 v21, v82
	v_mov_b32_e32 v22, v82
	v_mov_b32_e32 v23, v82
	v_mov_b32_e32 v24, v82
	v_mov_b32_e32 v25, v82
	v_mov_b32_e32 v26, v82
	v_mov_b32_e32 v27, v82
	v_mov_b32_e32 v28, v82
	v_mov_b32_e32 v29, v82
	v_mov_b32_e32 v30, v82
	v_mov_b32_e32 v31, v82
	v_mov_b32_e32 v32, v82
	v_mov_b32_e32 v33, v82
	v_mov_b32_e32 v2, v82
	v_mov_b32_e32 v3, v82
	v_mov_b32_e32 v4, v82
	v_mov_b32_e32 v5, v82
	v_mov_b32_e32 v6, v82
	v_mov_b32_e32 v7, v82
	v_mov_b32_e32 v8, v82
	v_mov_b32_e32 v9, v82
	v_mov_b32_e32 v10, v82
	v_mov_b32_e32 v11, v82
	v_mov_b32_e32 v12, v82
	v_mov_b32_e32 v13, v82
	v_mov_b32_e32 v14, v82
	v_mov_b32_e32 v15, v82
	v_mov_b32_e32 v16, v82
	v_mov_b32_e32 v17, v82
	v_mov_b32_e32 v116, v82
	v_mov_b32_e32 v117, v82
	v_mov_b32_e32 v118, v82
	v_mov_b32_e32 v119, v82
	v_mov_b32_e32 v120, v82
	v_mov_b32_e32 v121, v82
	v_mov_b32_e32 v122, v82
	v_mov_b32_e32 v123, v82
	v_mov_b32_e32 v124, v82
	v_mov_b32_e32 v125, v82
	v_mov_b32_e32 v126, v82
	v_mov_b32_e32 v127, v82
	v_mov_b32_e32 v128, v82
	v_mov_b32_e32 v129, v82
	v_mov_b32_e32 v98, v82
	v_mov_b32_e32 v99, v82
	v_mov_b32_e32 v100, v82
	v_mov_b32_e32 v101, v82
	v_mov_b32_e32 v102, v82
	v_mov_b32_e32 v103, v82
	v_mov_b32_e32 v104, v82
	v_mov_b32_e32 v105, v82
	v_mov_b32_e32 v106, v82
	v_mov_b32_e32 v107, v82
	v_mov_b32_e32 v108, v82
	v_mov_b32_e32 v109, v82
	v_mov_b32_e32 v110, v82
	v_mov_b32_e32 v111, v82
	v_mov_b32_e32 v112, v82
	v_mov_b32_e32 v113, v82
	v_mov_b32_e32 v50, v82
	v_mov_b32_e32 v51, v82
	v_mov_b32_e32 v52, v82
	v_mov_b32_e32 v53, v82
	v_mov_b32_e32 v54, v82
	v_mov_b32_e32 v55, v82
	v_mov_b32_e32 v56, v82
	v_mov_b32_e32 v57, v82
	v_mov_b32_e32 v58, v82
	v_mov_b32_e32 v59, v82
	v_mov_b32_e32 v60, v82
	v_mov_b32_e32 v61, v82
	v_mov_b32_e32 v62, v82
	v_mov_b32_e32 v63, v82
	v_mov_b32_e32 v64, v82
	v_mov_b32_e32 v65, v82
	v_mov_b32_e32 v34, v82
	v_mov_b32_e32 v35, v82
	v_mov_b32_e32 v36, v82
	v_mov_b32_e32 v37, v82
	v_mov_b32_e32 v38, v82
	v_mov_b32_e32 v39, v82
	v_mov_b32_e32 v40, v82
	v_mov_b32_e32 v41, v82
	v_mov_b32_e32 v42, v82
	v_mov_b32_e32 v43, v82
	v_mov_b32_e32 v44, v82
	v_mov_b32_e32 v45, v82
	v_mov_b32_e32 v46, v82
	v_mov_b32_e32 v47, v82
	v_mov_b32_e32 v48, v82
	v_mov_b32_e32 v49, v82
	s_waitcnt lgkmcnt(0)
	s_barrier
	s_add_u32 s18, s6, 0xd800080
	s_addc_u32 s19, s7, 0
	s_add_u32 s22, s18, 0x20000
	s_addc_u32 s23, s19, 0
	s_add_u32 s24, s18, 0x40000
	s_addc_u32 s25, s19, 0
	s_add_u32 s26, s18, 0x60000
	s_addc_u32 s27, s19, 0
	s_add_u32 s6, s8, 0x5600080
	s_addc_u32 s7, s9, 0
	s_add_u32 s8, s6, 0x20000
	s_addc_u32 s9, s7, 0
	s_add_u32 s10, s6, 0x40000
	s_addc_u32 s11, s7, 0
	s_add_u32 s12, s6, 0x60000
	s_addc_u32 s13, s7, 0
	v_lshrrev_b32_e32 v170, 3, v204
	v_lshrrev_b32_e32 v171, 4, v204
	v_xor_b32_e32 v171, v171, v204
	v_and_b32_e32 v171, 7, v171
	v_lshlrev_b32_e32 v171, 4, v171
	v_lshl_or_b32 v170, v170, 11, v171
	v_readfirstlane_b32 s28, v204
	s_and_b32 s28, s28, 0x3c0
	s_lshl_b32 s28, s28, 4
	s_mov_b32 s3, 0
	s_cmp_ge_u32 s28, 0x1000
	s_cbranch_scc0 .Lg_cout_noprio
	s_setprio 1
.Lg_cout_noprio:
	ds_read_b128 v[130:133], v190
	ds_read_b128 v[138:141], v186
	ds_read_b128 v[134:137], v190 offset:4096
	ds_read_b128 v[142:145], v186 offset:4096
	ds_read_b128 v[146:149], v186 offset:8192
	ds_read_b128 v[150:153], v186 offset:12288
	s_add_u32 m0, s28, 0x8000
	s_nop 0
	global_load_lds_dwordx4 v170, s[6:7]
	s_add_u32 m0, s28, 0x18000
	s_nop 0
	global_load_lds_dwordx4 v170, s[18:19]
	s_add_u32 m0, s28, 0xa000
	s_nop 0
	global_load_lds_dwordx4 v170, s[8:9]
	s_add_u32 m0, s28, 0x1a000
	s_nop 0
	global_load_lds_dwordx4 v170, s[22:23]
	s_add_u32 m0, s28, 0xc000
	s_nop 0
	global_load_lds_dwordx4 v170, s[10:11]
	s_add_u32 m0, s28, 0x1c000
	s_nop 0
	global_load_lds_dwordx4 v170, s[24:25]
	s_add_u32 m0, s28, 0xe000
	s_nop 0
	global_load_lds_dwordx4 v170, s[12:13]
	s_add_u32 m0, s28, 0x1e000
	s_nop 0
	global_load_lds_dwordx4 v170, s[26:27]
	s_branch .Lg_cout_mid

.Lg_cout_join:
	ds_read_b128 v[154:157], v191 offset:32768
	ds_read_b128 v[162:165], v195
	ds_read_b128 v[158:161], v191 offset:36864
	ds_read_b128 v[166:169], v195 offset:4096
	ds_read_b128 v[200:203], v195 offset:8192
	ds_read_b128 v[216:219], v195 offset:12288
	s_waitcnt lgkmcnt(6)
	v_mfma_f32_32x32x16_bf16 v[82:97], v[130:133], v[138:141], v[82:97]
	s_add_u32 s6, s6, 0x80
	s_addc_u32 s7, s7, 0
	v_mfma_f32_32x32x16_bf16 v[114:129], v[134:137], v[138:141], v[114:129]
	s_add_u32 s8, s8, 0x80
	s_addc_u32 s9, s9, 0
	v_mfma_f32_32x32x16_bf16 v[66:81], v[130:133], v[142:145], v[66:81]
	s_add_u32 s10, s10, 0x80
	s_addc_u32 s11, s11, 0
	v_mfma_f32_32x32x16_bf16 v[98:113], v[134:137], v[142:145], v[98:113]
	s_add_u32 s12, s12, 0x80
	s_addc_u32 s13, s13, 0
	v_mfma_f32_32x32x16_bf16 v[18:33], v[130:133], v[146:149], v[18:33]
	s_add_u32 s18, s18, 0x80
	s_addc_u32 s19, s19, 0
	v_mfma_f32_32x32x16_bf16 v[50:65], v[134:137], v[146:149], v[50:65]
	s_add_u32 s22, s22, 0x80
	s_addc_u32 s23, s23, 0
	v_mfma_f32_32x32x16_bf16 v[2:17], v[130:133], v[150:153], v[2:17]
	s_add_u32 s24, s24, 0x80
	s_addc_u32 s25, s25, 0
	v_mfma_f32_32x32x16_bf16 v[34:49], v[134:137], v[150:153], v[34:49]
	s_add_u32 s26, s26, 0x80
	s_addc_u32 s27, s27, 0
	ds_read_b128 v[130:133], v192 offset:32768
	ds_read_b128 v[138:141], v196
	ds_read_b128 v[134:137], v192 offset:36864
	ds_read_b128 v[142:145], v196 offset:4096
	ds_read_b128 v[146:149], v196 offset:8192
	ds_read_b128 v[150:153], v196 offset:12288
	s_waitcnt lgkmcnt(6)
	v_mfma_f32_32x32x16_bf16 v[82:97], v[154:157], v[162:165], v[82:97]
	v_mfma_f32_32x32x16_bf16 v[114:129], v[158:161], v[162:165], v[114:129]
	v_mfma_f32_32x32x16_bf16 v[66:81], v[154:157], v[166:169], v[66:81]
	v_mfma_f32_32x32x16_bf16 v[98:113], v[158:161], v[166:169], v[98:113]
	v_mfma_f32_32x32x16_bf16 v[18:33], v[154:157], v[200:203], v[18:33]
	v_mfma_f32_32x32x16_bf16 v[50:65], v[158:161], v[200:203], v[50:65]
	v_mfma_f32_32x32x16_bf16 v[2:17], v[154:157], v[216:219], v[2:17]
	v_mfma_f32_32x32x16_bf16 v[34:49], v[158:161], v[216:219], v[34:49]
	ds_read_b128 v[154:157], v193 offset:32768
	ds_read_b128 v[162:165], v197
	ds_read_b128 v[158:161], v193 offset:36864
	ds_read_b128 v[166:169], v197 offset:4096
	ds_read_b128 v[200:203], v197 offset:8192
	ds_read_b128 v[216:219], v197 offset:12288
	s_waitcnt lgkmcnt(6)
	v_mfma_f32_32x32x16_bf16 v[82:97], v[130:133], v[138:141], v[82:97]
	v_mfma_f32_32x32x16_bf16 v[114:129], v[134:137], v[138:141], v[114:129]
	v_mfma_f32_32x32x16_bf16 v[66:81], v[130:133], v[142:145], v[66:81]
	v_mfma_f32_32x32x16_bf16 v[98:113], v[134:137], v[142:145], v[98:113]
	v_mfma_f32_32x32x16_bf16 v[18:33], v[130:133], v[146:149], v[18:33]
	v_mfma_f32_32x32x16_bf16 v[50:65], v[134:137], v[146:149], v[50:65]
	v_mfma_f32_32x32x16_bf16 v[2:17], v[130:133], v[150:153], v[2:17]
	v_mfma_f32_32x32x16_bf16 v[34:49], v[134:137], v[150:153], v[34:49]
	s_waitcnt vmcnt(0) lgkmcnt(0)
	s_barrier
	s_add_i32 s3, s3, 2
	s_cmp_lt_u32 s3, 16
	s_cbranch_scc1 .Lg_cout_top
	v_mfma_f32_32x32x16_bf16 v[82:97], v[154:157], v[162:165], v[82:97]
	v_mfma_f32_32x32x16_bf16 v[114:129], v[158:161], v[162:165], v[114:129]
	v_mfma_f32_32x32x16_bf16 v[66:81], v[154:157], v[166:169], v[66:81]
	v_mfma_f32_32x32x16_bf16 v[98:113], v[158:161], v[166:169], v[98:113]
	v_mfma_f32_32x32x16_bf16 v[18:33], v[154:157], v[200:203], v[18:33]
	v_mfma_f32_32x32x16_bf16 v[50:65], v[158:161], v[200:203], v[50:65]
	v_mfma_f32_32x32x16_bf16 v[2:17], v[154:157], v[216:219], v[2:17]
	v_mfma_f32_32x32x16_bf16 v[34:49], v[158:161], v[216:219], v[34:49]
	s_nop 7
	s_nop 7
	s_setprio 0
	s_branch .LBB0_1141

.LBB0_1243:
	s_or_b64 exec, exec, s[10:11]
	v_readlane_b32 s12, v250, 9
	v_readlane_b32 s14, v250, 11
	v_readlane_b32 s15, v250, 12
	s_add_u32 s8, s14, s8
	s_addc_u32 s9, s15, s9
	s_add_u32 s10, s18, s0
	v_mov_b32_e32 v98, 0
	s_addc_u32 s11, s19, s1
	s_mov_b32 s3, 0
	v_mov_b32_e32 v99, v98
	v_mov_b32_e32 v100, v98
	v_mov_b32_e32 v101, v98
	v_mov_b32_e32 v102, v98
	v_mov_b32_e32 v103, v98
	v_mov_b32_e32 v104, v98
	v_mov_b32_e32 v105, v98
	v_mov_b32_e32 v106, v98
	v_mov_b32_e32 v107, v98
	v_mov_b32_e32 v108, v98
	v_mov_b32_e32 v109, v98
	v_mov_b32_e32 v110, v98
	v_mov_b32_e32 v111, v98
	v_mov_b32_e32 v112, v98
	v_mov_b32_e32 v113, v98
	v_mov_b32_e32 v82, v98
	v_mov_b32_e32 v83, v98
	v_mov_b32_e32 v84, v98
	v_mov_b32_e32 v85, v98
	v_mov_b32_e32 v86, v98
	v_mov_b32_e32 v87, v98
	v_mov_b32_e32 v88, v98
	v_mov_b32_e32 v89, v98
	v_mov_b32_e32 v90, v98
	v_mov_b32_e32 v91, v98
	v_mov_b32_e32 v92, v98
	v_mov_b32_e32 v93, v98
	v_mov_b32_e32 v94, v98
	v_mov_b32_e32 v95, v98
	v_mov_b32_e32 v96, v98
	v_mov_b32_e32 v97, v98
	v_mov_b32_e32 v34, v98
	v_mov_b32_e32 v35, v98
	v_mov_b32_e32 v36, v98
	v_mov_b32_e32 v37, v98
	v_mov_b32_e32 v38, v98
	v_mov_b32_e32 v39, v98
	v_mov_b32_e32 v40, v98
	v_mov_b32_e32 v41, v98
	v_mov_b32_e32 v42, v98
	v_mov_b32_e32 v43, v98
	v_mov_b32_e32 v44, v98
	v_mov_b32_e32 v45, v98
	v_mov_b32_e32 v46, v98
	v_mov_b32_e32 v47, v98
	v_mov_b32_e32 v48, v98
	v_mov_b32_e32 v49, v98
	v_mov_b32_e32 v18, v98
	v_mov_b32_e32 v19, v98
	v_mov_b32_e32 v20, v98
	v_mov_b32_e32 v21, v98
	v_mov_b32_e32 v22, v98
	v_mov_b32_e32 v23, v98
	v_mov_b32_e32 v24, v98
	v_mov_b32_e32 v25, v98
	v_mov_b32_e32 v26, v98
	v_mov_b32_e32 v27, v98
	v_mov_b32_e32 v28, v98
	v_mov_b32_e32 v29, v98
	v_mov_b32_e32 v30, v98
	v_mov_b32_e32 v31, v98
	v_mov_b32_e32 v32, v98
	v_mov_b32_e32 v33, v98
	v_mov_b32_e32 v114, v98
	v_mov_b32_e32 v115, v98
	v_mov_b32_e32 v116, v98
	v_mov_b32_e32 v117, v98
	v_mov_b32_e32 v118, v98
	v_mov_b32_e32 v119, v98
	v_mov_b32_e32 v120, v98
	v_mov_b32_e32 v121, v98
	v_mov_b32_e32 v122, v98
	v_mov_b32_e32 v123, v98
	v_mov_b32_e32 v124, v98
	v_mov_b32_e32 v125, v98
	v_mov_b32_e32 v126, v98
	v_mov_b32_e32 v127, v98
	v_mov_b32_e32 v128, v98
	v_mov_b32_e32 v129, v98
	v_mov_b32_e32 v66, v98
	v_mov_b32_e32 v67, v98
	v_mov_b32_e32 v68, v98
	v_mov_b32_e32 v69, v98
	v_mov_b32_e32 v70, v98
	v_mov_b32_e32 v71, v98
	v_mov_b32_e32 v72, v98
	v_mov_b32_e32 v73, v98
	v_mov_b32_e32 v74, v98
	v_mov_b32_e32 v75, v98
	v_mov_b32_e32 v76, v98
	v_mov_b32_e32 v77, v98
	v_mov_b32_e32 v78, v98
	v_mov_b32_e32 v79, v98
	v_mov_b32_e32 v80, v98
	v_mov_b32_e32 v81, v98
	v_mov_b32_e32 v50, v98
	v_mov_b32_e32 v51, v98
	v_mov_b32_e32 v52, v98
	v_mov_b32_e32 v53, v98
	v_mov_b32_e32 v54, v98
	v_mov_b32_e32 v55, v98
	v_mov_b32_e32 v56, v98
	v_mov_b32_e32 v57, v98
	v_mov_b32_e32 v58, v98
	v_mov_b32_e32 v59, v98
	v_mov_b32_e32 v60, v98
	v_mov_b32_e32 v61, v98
	v_mov_b32_e32 v62, v98
	v_mov_b32_e32 v63, v98
	v_mov_b32_e32 v64, v98
	v_mov_b32_e32 v65, v98
	v_mov_b32_e32 v2, v98
	v_mov_b32_e32 v3, v98
	v_mov_b32_e32 v4, v98
	v_mov_b32_e32 v5, v98
	v_mov_b32_e32 v6, v98
	v_mov_b32_e32 v7, v98
	v_mov_b32_e32 v8, v98
	v_mov_b32_e32 v9, v98
	v_mov_b32_e32 v10, v98
	v_mov_b32_e32 v11, v98
	v_mov_b32_e32 v12, v98
	v_mov_b32_e32 v13, v98
	v_mov_b32_e32 v14, v98
	v_mov_b32_e32 v15, v98
	v_mov_b32_e32 v16, v98
	v_mov_b32_e32 v17, v98
	v_readlane_b32 s13, v250, 10
	s_add_u32 s22, s8, 0x5800080
	s_addc_u32 s23, s9, 0
	s_add_u32 s24, s22, 0x20000
	s_addc_u32 s25, s23, 0
	s_add_u32 s26, s22, 0x40000
	s_addc_u32 s27, s23, 0
	s_add_u32 s28, s22, 0x60000
	s_addc_u32 s29, s23, 0
	s_add_u32 s8, s10, 0x4000080
	s_addc_u32 s9, s11, 0
	s_add_u32 s10, s8, 0x20000
	s_addc_u32 s11, s9, 0
	s_add_u32 s12, s8, 0x40000
	s_addc_u32 s13, s9, 0
	s_add_u32 s14, s8, 0x60000
	s_addc_u32 s15, s9, 0
	v_lshrrev_b32_e32 v170, 3, v204
	v_lshrrev_b32_e32 v171, 4, v204
	v_xor_b32_e32 v171, v171, v204
	v_and_b32_e32 v171, 7, v171
	v_lshlrev_b32_e32 v171, 4, v171
	v_lshl_or_b32 v170, v170, 11, v171
	v_readfirstlane_b32 s30, v204
	s_and_b32 s30, s30, 0x3c0
	s_lshl_b32 s30, s30, 4
	s_mov_b32 s3, 0
	s_cmp_ge_u32 s30, 0x1000
	s_cbranch_scc0 .Lg_aqkv_noprio
	s_setprio 1
.Lg_aqkv_noprio:
	ds_read_b128 v[130:133], v220
	ds_read_b128 v[138:141], v203
	ds_read_b128 v[134:137], v220 offset:4096
	ds_read_b128 v[142:145], v203 offset:4096
	ds_read_b128 v[146:149], v203 offset:8192
	ds_read_b128 v[150:153], v203 offset:12288
	s_add_u32 m0, s30, 0x8000
	s_nop 0
	global_load_lds_dwordx4 v170, s[8:9]
	s_add_u32 m0, s30, 0x18000
	s_nop 0
	global_load_lds_dwordx4 v170, s[22:23]
	s_add_u32 m0, s30, 0xa000
	s_nop 0
	global_load_lds_dwordx4 v170, s[10:11]
	s_add_u32 m0, s30, 0x1a000
	s_nop 0
	global_load_lds_dwordx4 v170, s[24:25]
	s_add_u32 m0, s30, 0xc000
	s_nop 0
	global_load_lds_dwordx4 v170, s[12:13]
	s_add_u32 m0, s30, 0x1c000
	s_nop 0
	global_load_lds_dwordx4 v170, s[26:27]
	s_add_u32 m0, s30, 0xe000
	s_nop 0
	global_load_lds_dwordx4 v170, s[14:15]
	s_add_u32 m0, s30, 0x1e000
	s_nop 0
	global_load_lds_dwordx4 v170, s[28:29]
	s_branch .Lg_aqkv_mid

.Lg_aqkv_join:
	ds_read_b128 v[154:157], v221 offset:32768
	ds_read_b128 v[162:165], v225
	ds_read_b128 v[158:161], v221 offset:36864
	ds_read_b128 v[166:169], v225 offset:4096
	ds_read_b128 v[176:179], v225 offset:8192
	ds_read_b128 v[180:183], v225 offset:12288
	s_waitcnt lgkmcnt(6)
	v_mfma_f32_32x32x16_bf16 v[98:113], v[130:133], v[138:141], v[98:113]
	s_add_u32 s8, s8, 0x80
	s_addc_u32 s9, s9, 0
	v_mfma_f32_32x32x16_bf16 v[114:129], v[134:137], v[138:141], v[114:129]
	s_add_u32 s10, s10, 0x80
	s_addc_u32 s11, s11, 0
	v_mfma_f32_32x32x16_bf16 v[82:97], v[130:133], v[142:145], v[82:97]
	s_add_u32 s12, s12, 0x80
	s_addc_u32 s13, s13, 0
	v_mfma_f32_32x32x16_bf16 v[66:81], v[134:137], v[142:145], v[66:81]
	s_add_u32 s14, s14, 0x80
	s_addc_u32 s15, s15, 0
	v_mfma_f32_32x32x16_bf16 v[34:49], v[130:133], v[146:149], v[34:49]
	s_add_u32 s22, s22, 0x80
	s_addc_u32 s23, s23, 0
	v_mfma_f32_32x32x16_bf16 v[50:65], v[134:137], v[146:149], v[50:65]
	s_add_u32 s24, s24, 0x80
	s_addc_u32 s25, s25, 0
	v_mfma_f32_32x32x16_bf16 v[18:33], v[130:133], v[150:153], v[18:33]
	s_add_u32 s26, s26, 0x80
	s_addc_u32 s27, s27, 0
	v_mfma_f32_32x32x16_bf16 v[2:17], v[134:137], v[150:153], v[2:17]
	s_add_u32 s28, s28, 0x80
	s_addc_u32 s29, s29, 0
	ds_read_b128 v[130:133], v222 offset:32768
	ds_read_b128 v[138:141], v226
	ds_read_b128 v[134:137], v222 offset:36864
	ds_read_b128 v[142:145], v226 offset:4096
	ds_read_b128 v[146:149], v226 offset:8192
	ds_read_b128 v[150:153], v226 offset:12288
	s_waitcnt lgkmcnt(6)
	v_mfma_f32_32x32x16_bf16 v[98:113], v[154:157], v[162:165], v[98:113]
	v_mfma_f32_32x32x16_bf16 v[114:129], v[158:161], v[162:165], v[114:129]
	v_mfma_f32_32x32x16_bf16 v[82:97], v[154:157], v[166:169], v[82:97]
	v_mfma_f32_32x32x16_bf16 v[66:81], v[158:161], v[166:169], v[66:81]
	v_mfma_f32_32x32x16_bf16 v[34:49], v[154:157], v[176:179], v[34:49]
	v_mfma_f32_32x32x16_bf16 v[50:65], v[158:161], v[176:179], v[50:65]
	v_mfma_f32_32x32x16_bf16 v[18:33], v[154:157], v[180:183], v[18:33]
	v_mfma_f32_32x32x16_bf16 v[2:17], v[158:161], v[180:183], v[2:17]
	ds_read_b128 v[154:157], v223 offset:32768
	ds_read_b128 v[162:165], v227
	ds_read_b128 v[158:161], v223 offset:36864
	ds_read_b128 v[166:169], v227 offset:4096
	ds_read_b128 v[176:179], v227 offset:8192
	ds_read_b128 v[180:183], v227 offset:12288
	s_waitcnt lgkmcnt(6)
	v_mfma_f32_32x32x16_bf16 v[98:113], v[130:133], v[138:141], v[98:113]
	v_mfma_f32_32x32x16_bf16 v[114:129], v[134:137], v[138:141], v[114:129]
	v_mfma_f32_32x32x16_bf16 v[82:97], v[130:133], v[142:145], v[82:97]
	v_mfma_f32_32x32x16_bf16 v[66:81], v[134:137], v[142:145], v[66:81]
	v_mfma_f32_32x32x16_bf16 v[34:49], v[130:133], v[146:149], v[34:49]
	v_mfma_f32_32x32x16_bf16 v[50:65], v[134:137], v[146:149], v[50:65]
	v_mfma_f32_32x32x16_bf16 v[18:33], v[130:133], v[150:153], v[18:33]
	v_mfma_f32_32x32x16_bf16 v[2:17], v[134:137], v[150:153], v[2:17]
	s_waitcnt vmcnt(0) lgkmcnt(0)
	s_barrier
	s_add_i32 s3, s3, 2
	s_cmp_lt_u32 s3, 16
	s_cbranch_scc1 .Lg_aqkv_top
	v_mfma_f32_32x32x16_bf16 v[98:113], v[154:157], v[162:165], v[98:113]
	v_mfma_f32_32x32x16_bf16 v[114:129], v[158:161], v[162:165], v[114:129]
	v_mfma_f32_32x32x16_bf16 v[82:97], v[154:157], v[166:169], v[82:97]
	v_mfma_f32_32x32x16_bf16 v[66:81], v[158:161], v[166:169], v[66:81]
	v_mfma_f32_32x32x16_bf16 v[34:49], v[154:157], v[176:179], v[34:49]
	v_mfma_f32_32x32x16_bf16 v[50:65], v[158:161], v[176:179], v[50:65]
	v_mfma_f32_32x32x16_bf16 v[18:33], v[154:157], v[180:183], v[18:33]
	v_mfma_f32_32x32x16_bf16 v[2:17], v[158:161], v[180:183], v[2:17]
	s_nop 7
	s_nop 7
	s_setprio 0
	s_branch .LBB0_1261

.LBB0_1508:
	s_bfe_u32 s4, s18, 0x20003
	s_lshr_b32 s0, s18, 5
	s_lshl_b32 s0, s0, 3
	s_and_b32 s1, s18, 7
	s_add_i32 s0, s0, s1
	s_lshl_b32 s2, s0, 8
	s_ashr_i32 s3, s2, 31
	s_ashr_i32 s5, s4, 31
	s_lshl_b64 s[0:1], s[4:5], 19
	s_lshl_b64 s[6:7], s[2:3], 11
	v_readlane_b32 s8, v252, 31
	v_readlane_b32 s9, v252, 32
	s_add_u32 s8, s8, s6
	v_mov_b32_e32 v34, v174
	s_addc_u32 s9, s9, s7
	s_add_u32 s10, s14, s0
	v_lshlrev_b32_e32 v0, 4, v34
	v_ashrrev_i32_e32 v35, 3, v34
	v_and_b32_e32 v0, 0x70, v0
	s_addc_u32 s11, s15, s1
	v_lshl_or_b32 v0, v35, 11, v0
	v_lshl_add_u64 v[26:27], s[10:11], 0, v[0:1]
	v_add_co_u32_e32 v10, vcc, s52, v26
	v_lshl_add_u64 v[28:29], s[8:9], 0, v[0:1]
	s_nop 0
	v_addc_co_u32_e32 v11, vcc, 0, v27, vcc
	v_add_co_u32_e32 v14, vcc, s52, v28
	global_load_dwordx4 v[2:5], v0, s[10:11]
	global_load_dwordx4 v[6:9], v0, s[8:9]
	v_addc_co_u32_e32 v15, vcc, 0, v29, vcc
	v_add_co_u32_e32 v18, vcc, s56, v26
	global_load_dwordx4 v[10:13], v[10:11], off
	s_nop 0
	global_load_dwordx4 v[14:17], v[14:15], off
	v_addc_co_u32_e32 v19, vcc, 0, v27, vcc
	v_add_co_u32_e32 v22, vcc, s56, v28
	v_readlane_b32 s8, v250, 9
	s_nop 0
	v_addc_co_u32_e32 v23, vcc, 0, v29, vcc
	v_add_co_u32_e32 v26, vcc, s57, v26
	global_load_dwordx4 v[18:21], v[18:19], off
	s_nop 0
	global_load_dwordx4 v[22:25], v[22:23], off
	v_addc_co_u32_e32 v27, vcc, 0, v27, vcc
	v_add_co_u32_e32 v30, vcc, s57, v28
	v_lshrrev_b32_e32 v36, 1, v35
	s_nop 0
	v_addc_co_u32_e32 v31, vcc, 0, v29, vcc
	global_load_dwordx4 v[26:29], v[26:27], off
	s_nop 0
	global_load_dwordx4 v[30:33], v[30:31], off
	v_readlane_b32 s10, v250, 11
	v_xor_b32_e32 v34, v36, v34
	v_readlane_b32 s11, v250, 12
	s_add_u32 s6, s10, s6
	v_lshlrev_b32_e32 v35, 7, v35
	v_lshlrev_b32_e32 v34, 4, v34
	s_addc_u32 s7, s11, s7
	v_mov_b32_e32 v82, 0
	v_and_or_b32 v198, v34, s55, v35
	v_readlane_b32 s9, v250, 10
	s_add_u32 s8, s16, s0
	s_mov_b32 s3, 0
	v_mov_b32_e32 v83, v82
	v_mov_b32_e32 v84, v82
	v_mov_b32_e32 v85, v82
	v_mov_b32_e32 v86, v82
	v_mov_b32_e32 v87, v82
	v_mov_b32_e32 v88, v82
	v_mov_b32_e32 v89, v82
	v_mov_b32_e32 v90, v82
	v_mov_b32_e32 v91, v82
	v_mov_b32_e32 v92, v82
	v_mov_b32_e32 v93, v82
	v_mov_b32_e32 v94, v82
	v_mov_b32_e32 v95, v82
	v_mov_b32_e32 v96, v82
	v_mov_b32_e32 v97, v82
	v_mov_b32_e32 v66, v82
	v_add_u32_e32 v199, 0x10000, v198
	s_addc_u32 s9, s17, s1
	v_mov_b32_e32 v67, v82
	v_mov_b32_e32 v68, v82
	v_mov_b32_e32 v69, v82
	v_mov_b32_e32 v70, v82
	v_mov_b32_e32 v71, v82
	v_mov_b32_e32 v72, v82
	v_mov_b32_e32 v73, v82
	v_mov_b32_e32 v74, v82
	v_mov_b32_e32 v75, v82
	v_mov_b32_e32 v76, v82
	v_mov_b32_e32 v77, v82
	v_mov_b32_e32 v78, v82
	v_mov_b32_e32 v79, v82
	v_mov_b32_e32 v80, v82
	v_mov_b32_e32 v81, v82
	v_mov_b32_e32 v114, v82
	v_mov_b32_e32 v115, v82
	v_mov_b32_e32 v116, v82
	v_mov_b32_e32 v117, v82
	s_waitcnt vmcnt(7)
	ds_write_b128 v198, v[2:5]
	s_waitcnt vmcnt(6)
	ds_write_b128 v199, v[6:9]
	s_waitcnt vmcnt(5)
	ds_write_b128 v198, v[10:13] offset:8192
	s_waitcnt vmcnt(4)
	ds_write_b128 v199, v[14:17] offset:8192
	s_waitcnt vmcnt(3)
	ds_write_b128 v198, v[18:21] offset:16384
	s_waitcnt vmcnt(2)
	ds_write_b128 v199, v[22:25] offset:16384
	s_waitcnt vmcnt(1)
	ds_write_b128 v198, v[26:29] offset:24576
	s_waitcnt vmcnt(0)
	ds_write_b128 v199, v[30:33] offset:24576
	v_mov_b32_e32 v18, v82
	v_mov_b32_e32 v19, v82
	v_mov_b32_e32 v20, v82
	v_mov_b32_e32 v21, v82
	v_mov_b32_e32 v22, v82
	v_mov_b32_e32 v23, v82
	v_mov_b32_e32 v24, v82
	v_mov_b32_e32 v25, v82
	v_mov_b32_e32 v26, v82
	v_mov_b32_e32 v27, v82
	v_mov_b32_e32 v28, v82
	v_mov_b32_e32 v29, v82
	v_mov_b32_e32 v30, v82
	v_mov_b32_e32 v31, v82
	v_mov_b32_e32 v32, v82
	v_mov_b32_e32 v33, v82
	v_mov_b32_e32 v2, v82
	v_mov_b32_e32 v3, v82
	v_mov_b32_e32 v4, v82
	v_mov_b32_e32 v5, v82
	v_mov_b32_e32 v6, v82
	v_mov_b32_e32 v7, v82
	v_mov_b32_e32 v8, v82
	v_mov_b32_e32 v9, v82
	v_mov_b32_e32 v10, v82
	v_mov_b32_e32 v11, v82
	v_mov_b32_e32 v12, v82
	v_mov_b32_e32 v13, v82
	v_mov_b32_e32 v14, v82
	v_mov_b32_e32 v15, v82
	v_mov_b32_e32 v16, v82
	v_mov_b32_e32 v17, v82
	v_mov_b32_e32 v118, v82
	v_mov_b32_e32 v119, v82
	v_mov_b32_e32 v120, v82
	v_mov_b32_e32 v121, v82
	v_mov_b32_e32 v122, v82
	v_mov_b32_e32 v123, v82
	v_mov_b32_e32 v124, v82
	v_mov_b32_e32 v125, v82
	v_mov_b32_e32 v126, v82
	v_mov_b32_e32 v127, v82
	v_mov_b32_e32 v128, v82
	v_mov_b32_e32 v129, v82
	v_mov_b32_e32 v98, v82
	v_mov_b32_e32 v99, v82
	v_mov_b32_e32 v100, v82
	v_mov_b32_e32 v101, v82
	v_mov_b32_e32 v102, v82
	v_mov_b32_e32 v103, v82
	v_mov_b32_e32 v104, v82
	v_mov_b32_e32 v105, v82
	v_mov_b32_e32 v106, v82
	v_mov_b32_e32 v107, v82
	v_mov_b32_e32 v108, v82
	v_mov_b32_e32 v109, v82
	v_mov_b32_e32 v110, v82
	v_mov_b32_e32 v111, v82
	v_mov_b32_e32 v112, v82
	v_mov_b32_e32 v113, v82
	v_mov_b32_e32 v50, v82
	v_mov_b32_e32 v51, v82
	v_mov_b32_e32 v52, v82
	v_mov_b32_e32 v53, v82
	v_mov_b32_e32 v54, v82
	v_mov_b32_e32 v55, v82
	v_mov_b32_e32 v56, v82
	v_mov_b32_e32 v57, v82
	v_mov_b32_e32 v58, v82
	v_mov_b32_e32 v59, v82
	v_mov_b32_e32 v60, v82
	v_mov_b32_e32 v61, v82
	v_mov_b32_e32 v62, v82
	v_mov_b32_e32 v63, v82
	v_mov_b32_e32 v64, v82
	v_mov_b32_e32 v65, v82
	v_mov_b32_e32 v34, v82
	v_mov_b32_e32 v35, v82
	v_mov_b32_e32 v36, v82
	v_mov_b32_e32 v37, v82
	v_mov_b32_e32 v38, v82
	v_mov_b32_e32 v39, v82
	v_mov_b32_e32 v40, v82
	v_mov_b32_e32 v41, v82
	v_mov_b32_e32 v42, v82
	v_mov_b32_e32 v43, v82
	v_mov_b32_e32 v44, v82
	v_mov_b32_e32 v45, v82
	v_mov_b32_e32 v46, v82
	v_mov_b32_e32 v47, v82
	v_mov_b32_e32 v48, v82
	v_mov_b32_e32 v49, v82
	s_waitcnt lgkmcnt(0)
	s_barrier
	s_add_u32 s22, s6, 0xd800080
	s_addc_u32 s23, s7, 0
	s_add_u32 s24, s22, 0x20000
	s_addc_u32 s25, s23, 0
	s_add_u32 s26, s22, 0x40000
	s_addc_u32 s27, s23, 0
	s_add_u32 s28, s22, 0x60000
	s_addc_u32 s29, s23, 0
	s_add_u32 s6, s8, 0x4c00080
	s_addc_u32 s7, s9, 0
	s_add_u32 s8, s6, 0x20000
	s_addc_u32 s9, s7, 0
	s_add_u32 s10, s6, 0x40000
	s_addc_u32 s11, s7, 0
	s_add_u32 s12, s6, 0x60000
	s_addc_u32 s13, s7, 0
	v_lshrrev_b32_e32 v170, 3, v204
	v_lshrrev_b32_e32 v171, 4, v204
	v_xor_b32_e32 v171, v171, v204
	v_and_b32_e32 v171, 7, v171
	v_lshlrev_b32_e32 v171, 4, v171
	v_lshl_or_b32 v170, v170, 11, v171
	v_readfirstlane_b32 s30, v204
	s_and_b32 s30, s30, 0x3c0
	s_lshl_b32 s30, s30, 4
	s_mov_b32 s3, 0
	s_cmp_ge_u32 s30, 0x1000
	s_cbranch_scc0 .Lg_aout_noprio
	s_setprio 1
.Lg_aout_noprio:
	ds_read_b128 v[130:133], v186
	ds_read_b128 v[138:141], v182
	ds_read_b128 v[134:137], v186 offset:4096
	ds_read_b128 v[142:145], v182 offset:4096
	ds_read_b128 v[146:149], v182 offset:8192
	ds_read_b128 v[150:153], v182 offset:12288
	s_add_u32 m0, s30, 0x8000
	s_nop 0
	global_load_lds_dwordx4 v170, s[6:7]
	s_add_u32 m0, s30, 0x18000
	s_nop 0
	global_load_lds_dwordx4 v170, s[22:23]
	s_add_u32 m0, s30, 0xa000
	s_nop 0
	global_load_lds_dwordx4 v170, s[8:9]
	s_add_u32 m0, s30, 0x1a000
	s_nop 0
	global_load_lds_dwordx4 v170, s[24:25]
	s_add_u32 m0, s30, 0xc000
	s_nop 0
	global_load_lds_dwordx4 v170, s[10:11]
	s_add_u32 m0, s30, 0x1c000
	s_nop 0
	global_load_lds_dwordx4 v170, s[26:27]
	s_add_u32 m0, s30, 0xe000
	s_nop 0
	global_load_lds_dwordx4 v170, s[12:13]
	s_add_u32 m0, s30, 0x1e000
	s_nop 0
	global_load_lds_dwordx4 v170, s[28:29]
	s_branch .Lg_aout_mid

.Lg_aout_join:
	ds_read_b128 v[154:157], v187 offset:32768
	ds_read_b128 v[162:165], v195
	ds_read_b128 v[158:161], v187 offset:36864
	ds_read_b128 v[166:169], v195 offset:4096
	ds_read_b128 v[200:203], v195 offset:8192
	ds_read_b128 v[216:219], v195 offset:12288
	s_waitcnt lgkmcnt(6)
	v_mfma_f32_32x32x16_bf16 v[82:97], v[130:133], v[138:141], v[82:97]
	s_add_u32 s6, s6, 0x80
	s_addc_u32 s7, s7, 0
	v_mfma_f32_32x32x16_bf16 v[114:129], v[134:137], v[138:141], v[114:129]
	s_add_u32 s8, s8, 0x80
	s_addc_u32 s9, s9, 0
	v_mfma_f32_32x32x16_bf16 v[66:81], v[130:133], v[142:145], v[66:81]
	s_add_u32 s10, s10, 0x80
	s_addc_u32 s11, s11, 0
	v_mfma_f32_32x32x16_bf16 v[98:113], v[134:137], v[142:145], v[98:113]
	s_add_u32 s12, s12, 0x80
	s_addc_u32 s13, s13, 0
	v_mfma_f32_32x32x16_bf16 v[18:33], v[130:133], v[146:149], v[18:33]
	s_add_u32 s22, s22, 0x80
	s_addc_u32 s23, s23, 0
	v_mfma_f32_32x32x16_bf16 v[50:65], v[134:137], v[146:149], v[50:65]
	s_add_u32 s24, s24, 0x80
	s_addc_u32 s25, s25, 0
	v_mfma_f32_32x32x16_bf16 v[2:17], v[130:133], v[150:153], v[2:17]
	s_add_u32 s26, s26, 0x80
	s_addc_u32 s27, s27, 0
	v_mfma_f32_32x32x16_bf16 v[34:49], v[134:137], v[150:153], v[34:49]
	s_add_u32 s28, s28, 0x80
	s_addc_u32 s29, s29, 0
	ds_read_b128 v[130:133], v192 offset:32768
	ds_read_b128 v[138:141], v196
	ds_read_b128 v[134:137], v192 offset:36864
	ds_read_b128 v[142:145], v196 offset:4096
	ds_read_b128 v[146:149], v196 offset:8192
	ds_read_b128 v[150:153], v196 offset:12288
	s_waitcnt lgkmcnt(6)
	v_mfma_f32_32x32x16_bf16 v[82:97], v[154:157], v[162:165], v[82:97]
	v_mfma_f32_32x32x16_bf16 v[114:129], v[158:161], v[162:165], v[114:129]
	v_mfma_f32_32x32x16_bf16 v[66:81], v[154:157], v[166:169], v[66:81]
	v_mfma_f32_32x32x16_bf16 v[98:113], v[158:161], v[166:169], v[98:113]
	v_mfma_f32_32x32x16_bf16 v[18:33], v[154:157], v[200:203], v[18:33]
	v_mfma_f32_32x32x16_bf16 v[50:65], v[158:161], v[200:203], v[50:65]
	v_mfma_f32_32x32x16_bf16 v[2:17], v[154:157], v[216:219], v[2:17]
	v_mfma_f32_32x32x16_bf16 v[34:49], v[158:161], v[216:219], v[34:49]
	ds_read_b128 v[154:157], v193 offset:32768
	ds_read_b128 v[162:165], v197
	ds_read_b128 v[158:161], v193 offset:36864
	ds_read_b128 v[166:169], v197 offset:4096
	ds_read_b128 v[200:203], v197 offset:8192
	ds_read_b128 v[216:219], v197 offset:12288
	s_waitcnt lgkmcnt(6)
	v_mfma_f32_32x32x16_bf16 v[82:97], v[130:133], v[138:141], v[82:97]
	v_mfma_f32_32x32x16_bf16 v[114:129], v[134:137], v[138:141], v[114:129]
	v_mfma_f32_32x32x16_bf16 v[66:81], v[130:133], v[142:145], v[66:81]
	v_mfma_f32_32x32x16_bf16 v[98:113], v[134:137], v[142:145], v[98:113]
	v_mfma_f32_32x32x16_bf16 v[18:33], v[130:133], v[146:149], v[18:33]
	v_mfma_f32_32x32x16_bf16 v[50:65], v[134:137], v[146:149], v[50:65]
	v_mfma_f32_32x32x16_bf16 v[2:17], v[130:133], v[150:153], v[2:17]
	v_mfma_f32_32x32x16_bf16 v[34:49], v[134:137], v[150:153], v[34:49]
	s_waitcnt vmcnt(0) lgkmcnt(0)
	s_barrier
	s_add_i32 s3, s3, 2
	s_cmp_lt_u32 s3, 16
	s_cbranch_scc1 .Lg_aout_top
	v_mfma_f32_32x32x16_bf16 v[82:97], v[154:157], v[162:165], v[82:97]
	v_mfma_f32_32x32x16_bf16 v[114:129], v[158:161], v[162:165], v[114:129]
	v_mfma_f32_32x32x16_bf16 v[66:81], v[154:157], v[166:169], v[66:81]
	v_mfma_f32_32x32x16_bf16 v[98:113], v[158:161], v[166:169], v[98:113]
	v_mfma_f32_32x32x16_bf16 v[18:33], v[154:157], v[200:203], v[18:33]
	v_mfma_f32_32x32x16_bf16 v[50:65], v[158:161], v[200:203], v[50:65]
	v_mfma_f32_32x32x16_bf16 v[2:17], v[154:157], v[216:219], v[2:17]
	v_mfma_f32_32x32x16_bf16 v[34:49], v[158:161], v[216:219], v[34:49]
	s_nop 7
	s_nop 7
	s_setprio 0
	s_branch .LBB0_1526

.LBB0_1604:
	s_or_b64 exec, exec, s[10:11]
	v_readlane_b32 s12, v250, 9
	v_readlane_b32 s14, v250, 11
	v_readlane_b32 s15, v250, 12
	s_add_u32 s8, s14, s8
	s_addc_u32 s9, s15, s9
	v_readlane_b32 s5, v252, 57
	s_add_u32 s10, s5, s0
	v_readlane_b32 s5, v252, 58
	s_addc_u32 s11, s5, s1
	v_readlane_b32 s5, v252, 59
	v_readlane_b32 s13, v250, 10
	s_add_u32 s12, s5, s0
	v_readlane_b32 s5, v252, 60
	s_addc_u32 s13, s5, s1
	v_readlane_b32 s5, v252, 61
	s_add_u32 s14, s5, s0
	v_readlane_b32 s5, v252, 62
	s_addc_u32 s15, s5, s1
	v_readlane_b32 s5, v252, 63
	s_add_u32 s16, s5, s0
	v_readlane_b32 s5, v251, 0
	s_addc_u32 s17, s5, s1
	v_readlane_b32 s5, v251, 1
	s_add_u32 s18, s5, s0
	v_readlane_b32 s5, v251, 2
	s_addc_u32 s19, s5, s1
	v_readlane_b32 s5, v251, 3
	s_add_u32 s20, s5, s0
	v_readlane_b32 s5, v251, 4
	s_addc_u32 s21, s5, s1
	v_readlane_b32 s5, v251, 5
	s_add_u32 s22, s5, s0
	v_readlane_b32 s5, v251, 6
	s_addc_u32 s23, s5, s1
	v_readlane_b32 s5, v251, 7
	s_add_u32 s24, s5, s0
	v_readlane_b32 s0, v251, 8
	v_mov_b32_e32 v98, 0
	s_addc_u32 s25, s0, s1
	s_mov_b32 s5, 0
	v_mov_b32_e32 v99, v98
	v_mov_b32_e32 v100, v98
	v_mov_b32_e32 v101, v98
	v_mov_b32_e32 v102, v98
	v_mov_b32_e32 v103, v98
	v_mov_b32_e32 v104, v98
	v_mov_b32_e32 v105, v98
	v_mov_b32_e32 v106, v98
	v_mov_b32_e32 v107, v98
	v_mov_b32_e32 v108, v98
	v_mov_b32_e32 v109, v98
	v_mov_b32_e32 v110, v98
	v_mov_b32_e32 v111, v98
	v_mov_b32_e32 v112, v98
	v_mov_b32_e32 v113, v98
	v_mov_b32_e32 v82, v98
	v_mov_b32_e32 v83, v98
	v_mov_b32_e32 v84, v98
	v_mov_b32_e32 v85, v98
	v_mov_b32_e32 v86, v98
	v_mov_b32_e32 v87, v98
	v_mov_b32_e32 v88, v98
	v_mov_b32_e32 v89, v98
	v_mov_b32_e32 v90, v98
	v_mov_b32_e32 v91, v98
	v_mov_b32_e32 v92, v98
	v_mov_b32_e32 v93, v98
	v_mov_b32_e32 v94, v98
	v_mov_b32_e32 v95, v98
	v_mov_b32_e32 v96, v98
	v_mov_b32_e32 v97, v98
	v_mov_b32_e32 v50, v98
	v_mov_b32_e32 v51, v98
	v_mov_b32_e32 v52, v98
	v_mov_b32_e32 v53, v98
	v_mov_b32_e32 v54, v98
	v_mov_b32_e32 v55, v98
	v_mov_b32_e32 v56, v98
	v_mov_b32_e32 v57, v98
	v_mov_b32_e32 v58, v98
	v_mov_b32_e32 v59, v98
	v_mov_b32_e32 v60, v98
	v_mov_b32_e32 v61, v98
	v_mov_b32_e32 v62, v98
	v_mov_b32_e32 v63, v98
	v_mov_b32_e32 v64, v98
	v_mov_b32_e32 v65, v98
	v_mov_b32_e32 v18, v98
	v_mov_b32_e32 v19, v98
	v_mov_b32_e32 v20, v98
	v_mov_b32_e32 v21, v98
	v_mov_b32_e32 v22, v98
	v_mov_b32_e32 v23, v98
	v_mov_b32_e32 v24, v98
	v_mov_b32_e32 v25, v98
	v_mov_b32_e32 v26, v98
	v_mov_b32_e32 v27, v98
	v_mov_b32_e32 v28, v98
	v_mov_b32_e32 v29, v98
	v_mov_b32_e32 v30, v98
	v_mov_b32_e32 v31, v98
	v_mov_b32_e32 v32, v98
	v_mov_b32_e32 v33, v98
	v_mov_b32_e32 v114, v98
	v_mov_b32_e32 v115, v98
	v_mov_b32_e32 v116, v98
	v_mov_b32_e32 v117, v98
	v_mov_b32_e32 v118, v98
	v_mov_b32_e32 v119, v98
	v_mov_b32_e32 v120, v98
	v_mov_b32_e32 v121, v98
	v_mov_b32_e32 v122, v98
	v_mov_b32_e32 v123, v98
	v_mov_b32_e32 v124, v98
	v_mov_b32_e32 v125, v98
	v_mov_b32_e32 v126, v98
	v_mov_b32_e32 v127, v98
	v_mov_b32_e32 v128, v98
	v_mov_b32_e32 v129, v98
	v_mov_b32_e32 v66, v98
	v_mov_b32_e32 v67, v98
	v_mov_b32_e32 v68, v98
	v_mov_b32_e32 v69, v98
	v_mov_b32_e32 v70, v98
	v_mov_b32_e32 v71, v98
	v_mov_b32_e32 v72, v98
	v_mov_b32_e32 v73, v98
	v_mov_b32_e32 v74, v98
	v_mov_b32_e32 v75, v98
	v_mov_b32_e32 v76, v98
	v_mov_b32_e32 v77, v98
	v_mov_b32_e32 v78, v98
	v_mov_b32_e32 v79, v98
	v_mov_b32_e32 v80, v98
	v_mov_b32_e32 v81, v98
	v_mov_b32_e32 v34, v98
	v_mov_b32_e32 v35, v98
	v_mov_b32_e32 v36, v98
	v_mov_b32_e32 v37, v98
	v_mov_b32_e32 v38, v98
	v_mov_b32_e32 v39, v98
	v_mov_b32_e32 v40, v98
	v_mov_b32_e32 v41, v98
	v_mov_b32_e32 v42, v98
	v_mov_b32_e32 v43, v98
	v_mov_b32_e32 v44, v98
	v_mov_b32_e32 v45, v98
	v_mov_b32_e32 v46, v98
	v_mov_b32_e32 v47, v98
	v_mov_b32_e32 v48, v98
	v_mov_b32_e32 v49, v98
	v_mov_b32_e32 v2, v98
	v_mov_b32_e32 v3, v98
	v_mov_b32_e32 v4, v98
	v_mov_b32_e32 v5, v98
	v_mov_b32_e32 v6, v98
	v_mov_b32_e32 v7, v98
	v_mov_b32_e32 v8, v98
	v_mov_b32_e32 v9, v98
	v_mov_b32_e32 v10, v98
	v_mov_b32_e32 v11, v98
	v_mov_b32_e32 v12, v98
	v_mov_b32_e32 v13, v98
	v_mov_b32_e32 v14, v98
	v_mov_b32_e32 v15, v98
	v_mov_b32_e32 v16, v98
	v_mov_b32_e32 v17, v98
	s_mov_b64 s[26:27], s[8:9]
	s_mov_b32 s8, s10
	s_mov_b32 s9, s11
	s_add_u32 s10, s8, 0x20000
	s_addc_u32 s11, s9, 0
	s_add_u32 s12, s8, 0x40000
	s_addc_u32 s13, s9, 0
	s_add_u32 s14, s8, 0x60000
	s_addc_u32 s15, s9, 0
	s_add_u32 s16, s26, 0x5800080
	s_addc_u32 s17, s27, 0
	s_add_u32 s18, s16, 0x20000
	s_addc_u32 s19, s17, 0
	s_add_u32 s20, s16, 0x40000
	s_addc_u32 s21, s17, 0
	s_add_u32 s22, s16, 0x60000
	s_addc_u32 s23, s17, 0
	v_lshrrev_b32_e32 v170, 3, v204
	v_lshrrev_b32_e32 v171, 4, v204
	v_xor_b32_e32 v171, v171, v204
	v_and_b32_e32 v171, 7, v171
	v_lshlrev_b32_e32 v171, 4, v171
	v_lshl_or_b32 v170, v170, 11, v171
	v_readfirstlane_b32 s24, v204
	s_and_b32 s24, s24, 0x3c0
	s_lshl_b32 s24, s24, 4
	s_mov_b32 s5, 0
	s_cmp_ge_u32 s24, 0x1000
	s_cbranch_scc0 .Lg_mlp1_noprio
	s_setprio 1
.Lg_mlp1_noprio:
	ds_read_b128 v[130:133], v186
	ds_read_b128 v[138:141], v181
	ds_read_b128 v[134:137], v186 offset:4096
	ds_read_b128 v[142:145], v181 offset:4096
	ds_read_b128 v[146:149], v181 offset:8192
	ds_read_b128 v[150:153], v181 offset:12288
	s_add_u32 m0, s24, 0x8000
	s_nop 0
	global_load_lds_dwordx4 v170, s[8:9]
	s_add_u32 m0, s24, 0x18000
	s_nop 0
	global_load_lds_dwordx4 v170, s[16:17]
	s_add_u32 m0, s24, 0xa000
	s_nop 0
	global_load_lds_dwordx4 v170, s[10:11]
	s_add_u32 m0, s24, 0x1a000
	s_nop 0
	global_load_lds_dwordx4 v170, s[18:19]
	s_add_u32 m0, s24, 0xc000
	s_nop 0
	global_load_lds_dwordx4 v170, s[12:13]
	s_add_u32 m0, s24, 0x1c000
	s_nop 0
	global_load_lds_dwordx4 v170, s[20:21]
	s_add_u32 m0, s24, 0xe000
	s_nop 0
	global_load_lds_dwordx4 v170, s[14:15]
	s_add_u32 m0, s24, 0x1e000
	s_nop 0
	global_load_lds_dwordx4 v170, s[22:23]
	s_branch .Lg_mlp1_mid

.Lg_mlp1_join:
	ds_read_b128 v[154:157], v187 offset:32768
	ds_read_b128 v[162:165], v191
	ds_read_b128 v[158:161], v187 offset:36864
	ds_read_b128 v[166:169], v191 offset:4096
	ds_read_b128 v[196:199], v191 offset:8192
	ds_read_b128 v[200:203], v191 offset:12288
	s_waitcnt lgkmcnt(6)
	v_mfma_f32_32x32x16_bf16 v[98:113], v[130:133], v[138:141], v[98:113]
	s_add_u32 s8, s8, 0x80
	s_addc_u32 s9, s9, 0
	v_mfma_f32_32x32x16_bf16 v[114:129], v[134:137], v[138:141], v[114:129]
	s_add_u32 s10, s10, 0x80
	s_addc_u32 s11, s11, 0
	v_mfma_f32_32x32x16_bf16 v[82:97], v[130:133], v[142:145], v[82:97]
	s_add_u32 s12, s12, 0x80
	s_addc_u32 s13, s13, 0
	v_mfma_f32_32x32x16_bf16 v[66:81], v[134:137], v[142:145], v[66:81]
	s_add_u32 s14, s14, 0x80
	s_addc_u32 s15, s15, 0
	v_mfma_f32_32x32x16_bf16 v[50:65], v[130:133], v[146:149], v[50:65]
	s_add_u32 s16, s16, 0x80
	s_addc_u32 s17, s17, 0
	v_mfma_f32_32x32x16_bf16 v[34:49], v[134:137], v[146:149], v[34:49]
	s_add_u32 s18, s18, 0x80
	s_addc_u32 s19, s19, 0
	v_mfma_f32_32x32x16_bf16 v[18:33], v[130:133], v[150:153], v[18:33]
	s_add_u32 s20, s20, 0x80
	s_addc_u32 s21, s21, 0
	v_mfma_f32_32x32x16_bf16 v[2:17], v[134:137], v[150:153], v[2:17]
	s_add_u32 s22, s22, 0x80
	s_addc_u32 s23, s23, 0
	ds_read_b128 v[130:133], v188 offset:32768
	ds_read_b128 v[138:141], v192
	ds_read_b128 v[134:137], v188 offset:36864
	ds_read_b128 v[142:145], v192 offset:4096
	ds_read_b128 v[146:149], v192 offset:8192
	ds_read_b128 v[150:153], v192 offset:12288
	s_waitcnt lgkmcnt(6)
	v_mfma_f32_32x32x16_bf16 v[98:113], v[154:157], v[162:165], v[98:113]
	v_mfma_f32_32x32x16_bf16 v[114:129], v[158:161], v[162:165], v[114:129]
	v_mfma_f32_32x32x16_bf16 v[82:97], v[154:157], v[166:169], v[82:97]
	v_mfma_f32_32x32x16_bf16 v[66:81], v[158:161], v[166:169], v[66:81]
	v_mfma_f32_32x32x16_bf16 v[50:65], v[154:157], v[196:199], v[50:65]
	v_mfma_f32_32x32x16_bf16 v[34:49], v[158:161], v[196:199], v[34:49]
	v_mfma_f32_32x32x16_bf16 v[18:33], v[154:157], v[200:203], v[18:33]
	v_mfma_f32_32x32x16_bf16 v[2:17], v[158:161], v[200:203], v[2:17]
	ds_read_b128 v[154:157], v189 offset:32768
	ds_read_b128 v[162:165], v193
	ds_read_b128 v[158:161], v189 offset:36864
	ds_read_b128 v[166:169], v193 offset:4096
	ds_read_b128 v[196:199], v193 offset:8192
	ds_read_b128 v[200:203], v193 offset:12288
	s_waitcnt lgkmcnt(6)
	v_mfma_f32_32x32x16_bf16 v[98:113], v[130:133], v[138:141], v[98:113]
	v_mfma_f32_32x32x16_bf16 v[114:129], v[134:137], v[138:141], v[114:129]
	v_mfma_f32_32x32x16_bf16 v[82:97], v[130:133], v[142:145], v[82:97]
	v_mfma_f32_32x32x16_bf16 v[66:81], v[134:137], v[142:145], v[66:81]
	v_mfma_f32_32x32x16_bf16 v[50:65], v[130:133], v[146:149], v[50:65]
	v_mfma_f32_32x32x16_bf16 v[34:49], v[134:137], v[146:149], v[34:49]
	v_mfma_f32_32x32x16_bf16 v[18:33], v[130:133], v[150:153], v[18:33]
	v_mfma_f32_32x32x16_bf16 v[2:17], v[134:137], v[150:153], v[2:17]
	s_waitcnt vmcnt(0) lgkmcnt(0)
	s_barrier
	s_add_i32 s5, s5, 2
	s_cmp_lt_u32 s5, 16
	s_cbranch_scc1 .Lg_mlp1_top
	v_mfma_f32_32x32x16_bf16 v[98:113], v[154:157], v[162:165], v[98:113]
	v_mfma_f32_32x32x16_bf16 v[114:129], v[158:161], v[162:165], v[114:129]
	v_mfma_f32_32x32x16_bf16 v[82:97], v[154:157], v[166:169], v[82:97]
	v_mfma_f32_32x32x16_bf16 v[66:81], v[158:161], v[166:169], v[66:81]
	v_mfma_f32_32x32x16_bf16 v[50:65], v[154:157], v[196:199], v[50:65]
	v_mfma_f32_32x32x16_bf16 v[34:49], v[158:161], v[196:199], v[34:49]
	v_mfma_f32_32x32x16_bf16 v[18:33], v[154:157], v[200:203], v[18:33]
	v_mfma_f32_32x32x16_bf16 v[2:17], v[158:161], v[200:203], v[2:17]
	s_nop 7
	s_nop 7
	s_setprio 0
	s_branch .LBB0_1601

.LBB0_1678:
	s_bfe_u32 s4, s30, 0x20003
	s_lshr_b32 s0, s30, 5
	s_lshl_b32 s0, s0, 3
	s_and_b32 s1, s30, 7
	s_add_i32 s0, s0, s1
	s_lshl_b32 s2, s0, 8
	s_ashr_i32 s3, s2, 31
	s_ashr_i32 s5, s4, 31
	s_lshl_b64 s[0:1], s[4:5], 21
	s_lshl_b64 s[6:7], s[2:3], 13
	v_readlane_b32 s8, v250, 48
	v_readlane_b32 s9, v250, 49
	s_add_u32 s8, s8, s6
	v_mov_b32_e32 v34, v172
	s_addc_u32 s9, s9, s7
	s_add_u32 s10, s28, s0
	v_lshlrev_b32_e32 v0, 4, v34
	v_ashrrev_i32_e32 v35, 3, v34
	v_and_b32_e32 v0, 0x70, v0
	s_addc_u32 s11, s29, s1
	v_lshl_or_b32 v0, v35, 13, v0
	v_lshl_add_u64 v[26:27], s[10:11], 0, v[0:1]
	s_mov_b32 s3, 0x80000
	v_add_co_u32_e32 v10, vcc, s3, v26
	v_lshl_add_u64 v[28:29], s[8:9], 0, v[0:1]
	s_nop 0
	v_addc_co_u32_e32 v11, vcc, 0, v27, vcc
	v_add_co_u32_e32 v14, vcc, s3, v28
	s_mov_b32 s3, 0x100000
	s_nop 0
	v_addc_co_u32_e32 v15, vcc, 0, v29, vcc
	v_add_co_u32_e32 v18, vcc, s3, v26
	global_load_dwordx4 v[2:5], v0, s[10:11]
	global_load_dwordx4 v[6:9], v0, s[8:9]
	v_addc_co_u32_e32 v19, vcc, 0, v27, vcc
	v_add_co_u32_e32 v22, vcc, s3, v28
	s_mov_b32 s3, 0x180000
	s_nop 0
	v_addc_co_u32_e32 v23, vcc, 0, v29, vcc
	v_add_co_u32_e32 v26, vcc, s3, v26
	global_load_dwordx4 v[10:13], v[10:11], off
	s_nop 0
	global_load_dwordx4 v[14:17], v[14:15], off
	v_addc_co_u32_e32 v27, vcc, 0, v27, vcc
	v_add_co_u32_e32 v30, vcc, s3, v28
	global_load_dwordx4 v[18:21], v[18:19], off
	s_nop 0
	global_load_dwordx4 v[22:25], v[22:23], off
	v_addc_co_u32_e32 v31, vcc, 0, v29, vcc
	global_load_dwordx4 v[26:29], v[26:27], off
	s_nop 0
	global_load_dwordx4 v[30:33], v[30:31], off
	v_readlane_b32 s8, v250, 9
	v_readlane_b32 s10, v250, 11
	v_readlane_b32 s11, v250, 12
	s_add_u32 s6, s10, s6
	s_addc_u32 s7, s11, s7
	v_readlane_b32 s5, v251, 9
	v_readlane_b32 s9, v250, 10
	s_add_u32 s8, s5, s0
	v_readlane_b32 s5, v251, 10
	s_addc_u32 s9, s5, s1
	v_readlane_b32 s5, v251, 11
	s_add_u32 s10, s5, s0
	v_readlane_b32 s5, v251, 12
	s_addc_u32 s11, s5, s1
	v_readlane_b32 s5, v251, 13
	s_add_u32 s12, s5, s0
	v_readlane_b32 s5, v251, 14
	s_addc_u32 s13, s5, s1
	v_readlane_b32 s5, v251, 15
	s_add_u32 s14, s5, s0
	v_readlane_b32 s5, v251, 16
	s_addc_u32 s15, s5, s1
	v_readlane_b32 s5, v251, 17
	s_add_u32 s16, s5, s0
	v_readlane_b32 s5, v251, 18
	s_addc_u32 s17, s5, s1
	v_readlane_b32 s5, v251, 19
	s_add_u32 s18, s5, s0
	v_readlane_b32 s5, v251, 20
	v_lshrrev_b32_e32 v36, 1, v35
	s_addc_u32 s19, s5, s1
	v_readlane_b32 s5, v251, 21
	v_xor_b32_e32 v34, v36, v34
	s_add_u32 s20, s5, s0
	v_readlane_b32 s5, v251, 22
	v_lshlrev_b32_e32 v35, 7, v35
	v_lshlrev_b32_e32 v34, 4, v34
	s_addc_u32 s21, s5, s1
	v_readlane_b32 s5, v251, 23
	v_mov_b32_e32 v66, 0
	v_and_or_b32 v192, v34, s55, v35
	s_add_u32 s22, s5, s0
	v_readlane_b32 s0, v251, 24
	s_mov_b32 s3, 0
	v_mov_b32_e32 v67, v66
	v_mov_b32_e32 v68, v66
	v_add_u32_e32 v193, 0x10000, v192
	s_addc_u32 s23, s0, s1
	s_waitcnt vmcnt(7)
	ds_write_b128 v192, v[2:5]
	s_waitcnt vmcnt(6)
	ds_write_b128 v193, v[6:9]
	s_waitcnt vmcnt(5)
	ds_write_b128 v192, v[10:13] offset:8192
	s_waitcnt vmcnt(4)
	ds_write_b128 v193, v[14:17] offset:8192
	s_waitcnt vmcnt(3)
	ds_write_b128 v192, v[18:21] offset:16384
	s_waitcnt vmcnt(2)
	ds_write_b128 v193, v[22:25] offset:16384
	s_waitcnt vmcnt(1)
	ds_write_b128 v192, v[26:29] offset:24576
	s_waitcnt vmcnt(0)
	ds_write_b128 v193, v[30:33] offset:24576
	v_mov_b32_e32 v69, v66
	v_mov_b32_e32 v70, v66
	v_mov_b32_e32 v71, v66
	v_mov_b32_e32 v72, v66
	v_mov_b32_e32 v73, v66
	v_mov_b32_e32 v74, v66
	v_mov_b32_e32 v75, v66
	v_mov_b32_e32 v76, v66
	v_mov_b32_e32 v77, v66
	v_mov_b32_e32 v78, v66
	v_mov_b32_e32 v79, v66
	v_mov_b32_e32 v80, v66
	v_mov_b32_e32 v81, v66
	v_mov_b32_e32 v82, v66
	v_mov_b32_e32 v83, v66
	v_mov_b32_e32 v84, v66
	v_mov_b32_e32 v85, v66
	v_mov_b32_e32 v86, v66
	v_mov_b32_e32 v87, v66
	v_mov_b32_e32 v88, v66
	v_mov_b32_e32 v89, v66
	v_mov_b32_e32 v90, v66
	v_mov_b32_e32 v91, v66
	v_mov_b32_e32 v92, v66
	v_mov_b32_e32 v93, v66
	v_mov_b32_e32 v94, v66
	v_mov_b32_e32 v95, v66
	v_mov_b32_e32 v96, v66
	v_mov_b32_e32 v97, v66
	v_mov_b32_e32 v18, v66
	v_mov_b32_e32 v19, v66
	v_mov_b32_e32 v20, v66
	v_mov_b32_e32 v21, v66
	v_mov_b32_e32 v22, v66
	v_mov_b32_e32 v23, v66
	v_mov_b32_e32 v24, v66
	v_mov_b32_e32 v25, v66
	v_mov_b32_e32 v26, v66
	v_mov_b32_e32 v27, v66
	v_mov_b32_e32 v28, v66
	v_mov_b32_e32 v29, v66
	v_mov_b32_e32 v30, v66
	v_mov_b32_e32 v31, v66
	v_mov_b32_e32 v32, v66
	v_mov_b32_e32 v33, v66
	v_mov_b32_e32 v2, v66
	v_mov_b32_e32 v3, v66
	v_mov_b32_e32 v4, v66
	v_mov_b32_e32 v5, v66
	v_mov_b32_e32 v6, v66
	v_mov_b32_e32 v7, v66
	v_mov_b32_e32 v8, v66
	v_mov_b32_e32 v9, v66
	v_mov_b32_e32 v10, v66
	v_mov_b32_e32 v11, v66
	v_mov_b32_e32 v12, v66
	v_mov_b32_e32 v13, v66
	v_mov_b32_e32 v14, v66
	v_mov_b32_e32 v15, v66
	v_mov_b32_e32 v16, v66
	v_mov_b32_e32 v17, v66
	v_mov_b32_e32 v114, v66
	v_mov_b32_e32 v115, v66
	v_mov_b32_e32 v116, v66
	v_mov_b32_e32 v117, v66
	v_mov_b32_e32 v118, v66
	v_mov_b32_e32 v119, v66
	v_mov_b32_e32 v120, v66
	v_mov_b32_e32 v121, v66
	v_mov_b32_e32 v122, v66
	v_mov_b32_e32 v123, v66
	v_mov_b32_e32 v124, v66
	v_mov_b32_e32 v125, v66
	v_mov_b32_e32 v126, v66
	v_mov_b32_e32 v127, v66
	v_mov_b32_e32 v128, v66
	v_mov_b32_e32 v129, v66
	v_mov_b32_e32 v98, v66
	v_mov_b32_e32 v99, v66
	v_mov_b32_e32 v100, v66
	v_mov_b32_e32 v101, v66
	v_mov_b32_e32 v102, v66
	v_mov_b32_e32 v103, v66
	v_mov_b32_e32 v104, v66
	v_mov_b32_e32 v105, v66
	v_mov_b32_e32 v106, v66
	v_mov_b32_e32 v107, v66
	v_mov_b32_e32 v108, v66
	v_mov_b32_e32 v109, v66
	v_mov_b32_e32 v110, v66
	v_mov_b32_e32 v111, v66
	v_mov_b32_e32 v112, v66
	v_mov_b32_e32 v113, v66
	v_mov_b32_e32 v50, v66
	v_mov_b32_e32 v51, v66
	v_mov_b32_e32 v52, v66
	v_mov_b32_e32 v53, v66
	v_mov_b32_e32 v54, v66
	v_mov_b32_e32 v55, v66
	v_mov_b32_e32 v56, v66
	v_mov_b32_e32 v57, v66
	v_mov_b32_e32 v58, v66
	v_mov_b32_e32 v59, v66
	v_mov_b32_e32 v60, v66
	v_mov_b32_e32 v61, v66
	v_mov_b32_e32 v62, v66
	v_mov_b32_e32 v63, v66
	v_mov_b32_e32 v64, v66
	v_mov_b32_e32 v65, v66
	v_mov_b32_e32 v34, v66
	v_mov_b32_e32 v35, v66
	v_mov_b32_e32 v36, v66
	v_mov_b32_e32 v37, v66
	v_mov_b32_e32 v38, v66
	v_mov_b32_e32 v39, v66
	v_mov_b32_e32 v40, v66
	v_mov_b32_e32 v41, v66
	v_mov_b32_e32 v42, v66
	v_mov_b32_e32 v43, v66
	v_mov_b32_e32 v44, v66
	v_mov_b32_e32 v45, v66
	v_mov_b32_e32 v46, v66
	v_mov_b32_e32 v47, v66
	v_mov_b32_e32 v48, v66
	v_mov_b32_e32 v49, v66
	s_waitcnt lgkmcnt(0)
	s_barrier
	s_add_u32 s10, s8, 0x80000
	s_addc_u32 s11, s9, 0
	s_add_u32 s12, s8, 0x100000
	s_addc_u32 s13, s9, 0
	s_add_u32 s14, s8, 0x180000
	s_addc_u32 s15, s9, 0
	s_add_u32 s16, s6, 0x7800080
	s_addc_u32 s17, s7, 0
	s_add_u32 s18, s16, 0x80000
	s_addc_u32 s19, s17, 0
	s_add_u32 s20, s16, 0x100000
	s_addc_u32 s21, s17, 0
	s_add_u32 s22, s16, 0x180000
	s_addc_u32 s23, s17, 0
	v_lshrrev_b32_e32 v170, 3, v204
	v_lshrrev_b32_e32 v171, 4, v204
	v_xor_b32_e32 v171, v171, v204
	v_and_b32_e32 v171, 7, v171
	v_lshlrev_b32_e32 v171, 4, v171
	v_lshl_or_b32 v170, v170, 13, v171
	v_readfirstlane_b32 s24, v204
	s_and_b32 s24, s24, 0x3c0
	s_lshl_b32 s24, s24, 4
	s_mov_b32 s3, 0
	s_cmp_ge_u32 s24, 0x1000
	s_cbranch_scc0 .Lg_mlp2_noprio
	s_setprio 1
.Lg_mlp2_noprio:
	ds_read_b128 v[130:133], v184
	ds_read_b128 v[138:141], v180
	ds_read_b128 v[134:137], v184 offset:4096
	ds_read_b128 v[142:145], v180 offset:4096
	ds_read_b128 v[146:149], v180 offset:8192
	ds_read_b128 v[150:153], v180 offset:12288
	s_add_u32 m0, s24, 0x8000
	s_nop 0
	global_load_lds_dwordx4 v170, s[8:9]
	s_add_u32 m0, s24, 0x18000
	s_nop 0
	global_load_lds_dwordx4 v170, s[16:17]
	s_add_u32 m0, s24, 0xa000
	s_nop 0
	global_load_lds_dwordx4 v170, s[10:11]
	s_add_u32 m0, s24, 0x1a000
	s_nop 0
	global_load_lds_dwordx4 v170, s[18:19]
	s_add_u32 m0, s24, 0xc000
	s_nop 0
	global_load_lds_dwordx4 v170, s[12:13]
	s_add_u32 m0, s24, 0x1c000
	s_nop 0
	global_load_lds_dwordx4 v170, s[20:21]
	s_add_u32 m0, s24, 0xe000
	s_nop 0
	global_load_lds_dwordx4 v170, s[14:15]
	s_add_u32 m0, s24, 0x1e000
	s_nop 0
	global_load_lds_dwordx4 v170, s[22:23]
	s_branch .Lg_mlp2_mid

.Lg_mlp2_join:
	ds_read_b128 v[154:157], v185 offset:32768
	ds_read_b128 v[162:165], v189
	ds_read_b128 v[158:161], v185 offset:36864
	ds_read_b128 v[166:169], v189 offset:4096
	ds_read_b128 v[194:197], v189 offset:8192
	ds_read_b128 v[198:201], v189 offset:12288
	s_waitcnt lgkmcnt(6)
	v_mfma_f32_32x32x16_bf16 v[66:81], v[130:133], v[138:141], v[66:81]
	s_add_u32 s8, s8, 0x80
	s_addc_u32 s9, s9, 0
	v_mfma_f32_32x32x16_bf16 v[114:129], v[134:137], v[138:141], v[114:129]
	s_add_u32 s10, s10, 0x80
	s_addc_u32 s11, s11, 0
	v_mfma_f32_32x32x16_bf16 v[82:97], v[130:133], v[142:145], v[82:97]
	s_add_u32 s12, s12, 0x80
	s_addc_u32 s13, s13, 0
	v_mfma_f32_32x32x16_bf16 v[98:113], v[134:137], v[142:145], v[98:113]
	s_add_u32 s14, s14, 0x80
	s_addc_u32 s15, s15, 0
	v_mfma_f32_32x32x16_bf16 v[18:33], v[130:133], v[146:149], v[18:33]
	s_add_u32 s16, s16, 0x80
	s_addc_u32 s17, s17, 0
	v_mfma_f32_32x32x16_bf16 v[50:65], v[134:137], v[146:149], v[50:65]
	s_add_u32 s18, s18, 0x80
	s_addc_u32 s19, s19, 0
	v_mfma_f32_32x32x16_bf16 v[2:17], v[130:133], v[150:153], v[2:17]
	s_add_u32 s20, s20, 0x80
	s_addc_u32 s21, s21, 0
	v_mfma_f32_32x32x16_bf16 v[34:49], v[134:137], v[150:153], v[34:49]
	s_add_u32 s22, s22, 0x80
	s_addc_u32 s23, s23, 0
	ds_read_b128 v[130:133], v186 offset:32768
	ds_read_b128 v[138:141], v190
	ds_read_b128 v[134:137], v186 offset:36864
	ds_read_b128 v[142:145], v190 offset:4096
	ds_read_b128 v[146:149], v190 offset:8192
	ds_read_b128 v[150:153], v190 offset:12288
	s_waitcnt lgkmcnt(6)
	v_mfma_f32_32x32x16_bf16 v[66:81], v[154:157], v[162:165], v[66:81]
	v_mfma_f32_32x32x16_bf16 v[114:129], v[158:161], v[162:165], v[114:129]
	v_mfma_f32_32x32x16_bf16 v[82:97], v[154:157], v[166:169], v[82:97]
	v_mfma_f32_32x32x16_bf16 v[98:113], v[158:161], v[166:169], v[98:113]
	v_mfma_f32_32x32x16_bf16 v[18:33], v[154:157], v[194:197], v[18:33]
	v_mfma_f32_32x32x16_bf16 v[50:65], v[158:161], v[194:197], v[50:65]
	v_mfma_f32_32x32x16_bf16 v[2:17], v[154:157], v[198:201], v[2:17]
	v_mfma_f32_32x32x16_bf16 v[34:49], v[158:161], v[198:201], v[34:49]
	ds_read_b128 v[154:157], v187 offset:32768
	ds_read_b128 v[162:165], v191
	ds_read_b128 v[158:161], v187 offset:36864
	ds_read_b128 v[166:169], v191 offset:4096
	ds_read_b128 v[194:197], v191 offset:8192
	ds_read_b128 v[198:201], v191 offset:12288
	s_waitcnt lgkmcnt(6)
	v_mfma_f32_32x32x16_bf16 v[66:81], v[130:133], v[138:141], v[66:81]
	v_mfma_f32_32x32x16_bf16 v[114:129], v[134:137], v[138:141], v[114:129]
	v_mfma_f32_32x32x16_bf16 v[82:97], v[130:133], v[142:145], v[82:97]
	v_mfma_f32_32x32x16_bf16 v[98:113], v[134:137], v[142:145], v[98:113]
	v_mfma_f32_32x32x16_bf16 v[18:33], v[130:133], v[146:149], v[18:33]
	v_mfma_f32_32x32x16_bf16 v[50:65], v[134:137], v[146:149], v[50:65]
	v_mfma_f32_32x32x16_bf16 v[2:17], v[130:133], v[150:153], v[2:17]
	v_mfma_f32_32x32x16_bf16 v[34:49], v[134:137], v[150:153], v[34:49]
	s_waitcnt vmcnt(0) lgkmcnt(0)
	s_barrier
	s_add_i32 s3, s3, 2
	s_cmp_lt_u32 s3, 64
	s_cbranch_scc1 .Lg_mlp2_top
	v_mfma_f32_32x32x16_bf16 v[66:81], v[154:157], v[162:165], v[66:81]
	v_mfma_f32_32x32x16_bf16 v[114:129], v[158:161], v[162:165], v[114:129]
	v_mfma_f32_32x32x16_bf16 v[82:97], v[154:157], v[166:169], v[82:97]
	v_mfma_f32_32x32x16_bf16 v[98:113], v[158:161], v[166:169], v[98:113]
	v_mfma_f32_32x32x16_bf16 v[18:33], v[154:157], v[194:197], v[18:33]
	v_mfma_f32_32x32x16_bf16 v[50:65], v[158:161], v[194:197], v[50:65]
	v_mfma_f32_32x32x16_bf16 v[2:17], v[154:157], v[198:201], v[2:17]
	v_mfma_f32_32x32x16_bf16 v[34:49], v[158:161], v[198:201], v[34:49]
	s_nop 7
	s_nop 7
	s_setprio 0
	s_branch .LBB0_1696
